# sample-FoX: QK / forget-bias / PV LDS fragment reads issued in batches ahead of use with counted lgkmcnt waits
# baseline (speedup 1.0000x reference)
.Lj2_lv_done:
.LBB0_1002:
	s_add_i32 s57, s43, s40
	s_cmpk_lt_i32 s57, 0x1040
	s_cselect_b64 s[8:9], -1, 0
	s_cmp_le_i32 s57, s51
	s_cselect_b64 s[58:59], -1, 0
	s_and_b64 s[58:59], s[8:9], s[58:59]
	v_cndmask_b32_e64 v154, 0, 1, s[58:59]
	v_cmp_ne_u32_e64 s[8:9], 1, v154
	s_andn2_b64 vcc, exec, s[58:59]
	s_cbranch_vccnz .LBB0_1008
	s_cmp_le_i32 s57, s56
	ds_read_b128 v[202:205], v178
	ds_read_b128 v[206:209], v178 offset:32
	ds_read_b128 v[210:213], v178 offset:64
	ds_read_b128 v[220:223], v178 offset:96
	ds_read_b128 v[182:185], v172
	ds_read_b128 v[224:227], v177
	ds_read_b128 v[186:189], v172 offset:1024
	ds_read_b128 v[228:231], v177 offset:32
	ds_read_b128 v[190:193], v172 offset:2048
	ds_read_b128 v[232:235], v177 offset:64
	ds_read_b128 v[194:197], v172 offset:3072
	ds_read_b128 v[236:239], v177 offset:96
	s_waitcnt lgkmcnt(8)
	v_sub_f32_e32 v168, v2, v202
	v_sub_f32_e32 v169, v1, v203
	v_sub_f32_e32 v200, v20, v204
	v_sub_f32_e32 v201, v3, v205
	v_sub_f32_e32 v164, v22, v206
	v_sub_f32_e32 v165, v21, v207
	v_sub_f32_e32 v162, v24, v208
	v_sub_f32_e32 v163, v23, v209
	v_sub_f32_e32 v160, v42, v210
	v_sub_f32_e32 v161, v25, v211
	v_sub_f32_e32 v158, v44, v212
	v_sub_f32_e32 v159, v43, v213
	v_sub_f32_e32 v166, v46, v220
	v_sub_f32_e32 v167, v45, v221
	v_sub_f32_e32 v170, v48, v222
	v_sub_f32_e32 v171, v47, v223
	ds_read_b128 v[202:205], v177 offset:4608
	ds_read_b128 v[206:209], v177 offset:4640
	ds_read_b128 v[210:213], v177 offset:4672
	ds_read_b128 v[220:223], v177 offset:4704
	s_waitcnt lgkmcnt(10)
	v_mfma_f32_32x32x16_bf16 v[50:65], v[224:227], v[182:185], 0
	s_waitcnt lgkmcnt(8)
	v_mfma_f32_32x32x16_bf16 v[50:65], v[228:231], v[186:189], v[50:65]
	s_waitcnt lgkmcnt(6)
	v_mfma_f32_32x32x16_bf16 v[50:65], v[232:235], v[190:193], v[50:65]
	s_waitcnt lgkmcnt(4)
	v_mfma_f32_32x32x16_bf16 v[50:65], v[236:239], v[194:197], v[50:65]
	ds_read_b128 v[224:227], v178 offset:128
	ds_read_b128 v[228:231], v178 offset:160
	ds_read_b128 v[232:235], v178 offset:192
	ds_read_b128 v[236:239], v178 offset:224
	s_nop 7
	v_pk_add_f32 v[168:169], v[50:51], v[168:169]
	v_pk_add_f32 v[156:157], v[62:63], v[166:167]
	v_pk_add_f32 v[166:167], v[52:53], v[200:201]
	v_pk_add_f32 v[154:155], v[64:65], v[170:171]
	v_pk_add_f32 v[158:159], v[60:61], v[158:159]
	v_pk_add_f32 v[160:161], v[58:59], v[160:161]
	v_pk_add_f32 v[162:163], v[56:57], v[162:163]
	v_pk_add_f32 v[164:165], v[54:55], v[164:165]
	s_waitcnt lgkmcnt(4)
	v_mfma_f32_32x32x16_bf16 v[50:65], v[202:205], v[182:185], 0
	v_mfma_f32_32x32x16_bf16 v[50:65], v[206:209], v[186:189], v[50:65]
	v_mfma_f32_32x32x16_bf16 v[50:65], v[210:213], v[190:193], v[50:65]
	v_mfma_f32_32x32x16_bf16 v[50:65], v[220:223], v[194:197], v[50:65]
	s_waitcnt lgkmcnt(0)
	v_sub_f32_e32 v186, v22, v228
	v_sub_f32_e32 v187, v21, v229
	v_sub_f32_e32 v188, v24, v230
	v_sub_f32_e32 v189, v23, v231
	v_sub_f32_e32 v190, v42, v232
	v_sub_f32_e32 v191, v25, v233
	v_sub_f32_e32 v192, v44, v234
	v_sub_f32_e32 v193, v43, v235
	v_sub_f32_e32 v194, v46, v236
	v_sub_f32_e32 v195, v45, v237
	v_sub_f32_e32 v196, v48, v238
	v_sub_f32_e32 v197, v47, v239
	v_sub_f32_e32 v170, v2, v224
	v_sub_f32_e32 v171, v1, v225
	v_sub_f32_e32 v184, v20, v226
	v_sub_f32_e32 v185, v3, v227
	v_pk_add_f32 v[56:57], v[56:57], v[188:189]
	v_pk_add_f32 v[54:55], v[54:55], v[186:187]
	v_pk_add_f32 v[60:61], v[60:61], v[192:193]
	v_pk_add_f32 v[58:59], v[58:59], v[190:191]
	v_pk_add_f32 v[62:63], v[62:63], v[194:195]
	v_pk_add_f32 v[170:171], v[50:51], v[170:171]
	v_pk_add_f32 v[50:51], v[64:65], v[196:197]
	v_pk_add_f32 v[52:53], v[52:53], v[184:185]
	s_cbranch_scc1 .LBB0_1005
	v_add_u32_e32 v64, s40, v132
	v_add_u32_e32 v65, 32, v64
	v_cmp_le_i32_e32 vcc, v65, v175
	v_add_u32_e32 v65, 33, v64
	s_nop 0
	v_cndmask_b32_e32 v170, v219, v170, vcc
	v_cmp_lt_i32_e32 vcc, v64, v175
	s_nop 1
	v_cndmask_b32_e32 v169, v219, v169, vcc
	v_cmp_le_i32_e32 vcc, v64, v175
	s_nop 1
	v_cndmask_b32_e32 v168, v219, v168, vcc
	v_cmp_le_i32_e32 vcc, v65, v175
	v_add_u32_e32 v65, 2, v64
	s_nop 0
	v_cndmask_b32_e32 v171, v219, v171, vcc
	v_cmp_le_i32_e32 vcc, v65, v175
	v_add_u32_e32 v65, 34, v64
	s_nop 0
	v_cndmask_b32_e32 v166, v219, v166, vcc
	v_cmp_le_i32_e32 vcc, v65, v175
	v_add_u32_e32 v65, 3, v64
	s_nop 0
	v_cndmask_b32_e32 v52, v219, v52, vcc
	v_cmp_le_i32_e32 vcc, v65, v175
	v_add_u32_e32 v65, 35, v64
	s_nop 0
	v_cndmask_b32_e32 v167, v219, v167, vcc
	v_cmp_le_i32_e32 vcc, v65, v175
	v_add_u32_e32 v65, 8, v64
	s_nop 0
	v_cndmask_b32_e32 v53, v219, v53, vcc
	v_cmp_le_i32_e32 vcc, v65, v175
	v_add_u32_e32 v65, 40, v64
	s_nop 0
	v_cndmask_b32_e32 v164, v219, v164, vcc
	v_cmp_le_i32_e32 vcc, v65, v175
	v_add_u32_e32 v65, 9, v64
	s_nop 0
	v_cndmask_b32_e32 v54, v219, v54, vcc
	v_cmp_le_i32_e32 vcc, v65, v175
	v_add_u32_e32 v65, 41, v64
	s_nop 0
	v_cndmask_b32_e32 v165, v219, v165, vcc
	v_cmp_le_i32_e32 vcc, v65, v175
	v_add_u32_e32 v65, 10, v64
	s_nop 0
	v_cndmask_b32_e32 v55, v219, v55, vcc
	v_cmp_le_i32_e32 vcc, v65, v175
	v_add_u32_e32 v65, 42, v64
	s_nop 0
	v_cndmask_b32_e32 v162, v219, v162, vcc
	v_cmp_le_i32_e32 vcc, v65, v175
	v_add_u32_e32 v65, 11, v64
	s_nop 0
	v_cndmask_b32_e32 v56, v219, v56, vcc
	v_cmp_le_i32_e32 vcc, v65, v175
	v_add_u32_e32 v65, 43, v64
	s_nop 0
	v_cndmask_b32_e32 v163, v219, v163, vcc
	v_cmp_le_i32_e32 vcc, v65, v175
	v_add_u32_e32 v65, 16, v64
	s_nop 0
	v_cndmask_b32_e32 v57, v219, v57, vcc
	v_cmp_le_i32_e32 vcc, v65, v175
	v_add_u32_e32 v65, 48, v64
	s_nop 0
	v_cndmask_b32_e32 v160, v219, v160, vcc
	v_cmp_le_i32_e32 vcc, v65, v175
	v_add_u32_e32 v65, 17, v64
	s_nop 0
	v_cndmask_b32_e32 v58, v219, v58, vcc
	v_cmp_le_i32_e32 vcc, v65, v175
	v_add_u32_e32 v65, 49, v64
	s_nop 0
	v_cndmask_b32_e32 v161, v219, v161, vcc
	v_cmp_le_i32_e32 vcc, v65, v175
	v_add_u32_e32 v65, 18, v64
	s_nop 0
	v_cndmask_b32_e32 v59, v219, v59, vcc
	v_cmp_le_i32_e32 vcc, v65, v175
	v_add_u32_e32 v65, 50, v64
	s_nop 0
	v_cndmask_b32_e32 v158, v219, v158, vcc
	v_cmp_le_i32_e32 vcc, v65, v175
	v_add_u32_e32 v65, 19, v64
	s_nop 0
	v_cndmask_b32_e32 v60, v219, v60, vcc
	v_cmp_le_i32_e32 vcc, v65, v175
	v_add_u32_e32 v65, 51, v64
	s_nop 0
	v_cndmask_b32_e32 v159, v219, v159, vcc
	v_cmp_le_i32_e32 vcc, v65, v175
	v_add_u32_e32 v65, 24, v64
	s_nop 0
	v_cndmask_b32_e32 v61, v219, v61, vcc
	v_cmp_le_i32_e32 vcc, v65, v175
	v_add_u32_e32 v65, 56, v64
	s_nop 0
	v_cndmask_b32_e32 v156, v219, v156, vcc
	v_cmp_le_i32_e32 vcc, v65, v175
	v_add_u32_e32 v65, 25, v64
	s_nop 0
	v_cndmask_b32_e32 v62, v219, v62, vcc
	v_cmp_le_i32_e32 vcc, v65, v175
	v_add_u32_e32 v65, 57, v64
	s_nop 0
	v_cndmask_b32_e32 v157, v219, v157, vcc
	v_cmp_le_i32_e32 vcc, v65, v175
	v_add_u32_e32 v65, 26, v64
	s_nop 0
	v_cndmask_b32_e32 v63, v219, v63, vcc
	v_cmp_le_i32_e32 vcc, v65, v175
	v_add_u32_e32 v65, 58, v64
	s_nop 0
	v_cndmask_b32_e32 v154, v219, v154, vcc
	v_cmp_le_i32_e32 vcc, v65, v175
	v_add_u32_e32 v65, 27, v64
	v_add_u32_e32 v64, 59, v64
	v_cndmask_b32_e32 v50, v219, v50, vcc
	v_cmp_le_i32_e32 vcc, v65, v175
	s_nop 1
	v_cndmask_b32_e32 v155, v219, v155, vcc
	v_cmp_le_i32_e32 vcc, v64, v175
	s_nop 1
	v_cndmask_b32_e32 v51, v219, v51, vcc

.LBB0_1007:
	v_sub_f32_e32 v65, v168, v182
	v_sub_f32_e32 v168, v170, v182
	v_exp_f32_e32 v65, v65
	v_exp_f32_e32 v168, v168
	v_sub_f32_e32 v169, v169, v182
	v_sub_f32_e32 v170, v171, v182
	v_exp_f32_e32 v169, v169
	v_exp_f32_e32 v170, v170
	v_sub_f32_e32 v166, v166, v182
	v_sub_f32_e32 v52, v52, v182
	v_exp_f32_e32 v166, v166
	v_exp_f32_e32 v183, v52
	v_sub_f32_e32 v52, v167, v182
	v_sub_f32_e32 v53, v53, v182
	v_exp_f32_e32 v52, v52
	v_exp_f32_e32 v167, v53
	v_add_f32_e32 v171, v168, v65
	v_add_f32_e32 v171, 0, v171
	v_add_f32_e32 v181, v170, v169
	v_sub_f32_e32 v164, v164, v182
	v_sub_f32_e32 v54, v54, v182
	v_add_f32_e32 v53, v181, v171
	v_add_f32_e32 v171, v183, v166
	v_exp_f32_e32 v164, v164
	v_exp_f32_e32 v181, v54
	v_sub_f32_e32 v54, v165, v182
	v_sub_f32_e32 v55, v55, v182
	v_add_f32_e32 v53, v171, v53
	v_add_f32_e32 v171, v167, v52
	v_exp_f32_e32 v54, v54
	v_exp_f32_e32 v165, v55
	v_sub_f32_e32 v162, v162, v182
	v_sub_f32_e32 v56, v56, v182
	v_add_f32_e32 v53, v171, v53
	v_exp_f32_e32 v162, v162
	v_exp_f32_e32 v171, v56
	v_sub_f32_e32 v56, v163, v182
	v_sub_f32_e32 v57, v57, v182
	v_exp_f32_e32 v56, v56
	v_exp_f32_e32 v57, v57
	v_sub_f32_e32 v160, v160, v182
	v_sub_f32_e32 v58, v58, v182
	v_add_f32_e32 v55, v181, v164
	v_exp_f32_e32 v160, v160
	v_exp_f32_e32 v163, v58
	v_sub_f32_e32 v58, v161, v182
	v_sub_f32_e32 v59, v59, v182
	v_add_f32_e32 v53, v55, v53
	v_add_f32_e32 v55, v165, v54
	v_exp_f32_e32 v58, v58
	v_exp_f32_e32 v161, v59
	v_sub_f32_e32 v59, v158, v182
	v_sub_f32_e32 v60, v60, v182
	v_add_f32_e32 v53, v55, v53
	v_add_f32_e32 v55, v171, v162
	v_exp_f32_e32 v59, v59
	v_exp_f32_e32 v158, v60
	v_sub_f32_e32 v60, v159, v182
	v_sub_f32_e32 v61, v61, v182
	v_add_f32_e32 v53, v55, v53
	v_add_f32_e32 v55, v57, v56
	v_exp_f32_e32 v60, v60
	v_exp_f32_e32 v159, v61
	v_sub_f32_e32 v61, v156, v182
	v_sub_f32_e32 v62, v62, v182
	v_add_f32_e32 v53, v55, v53
	v_add_f32_e32 v55, v163, v160
	v_exp_f32_e32 v61, v61
	v_exp_f32_e32 v156, v62
	v_sub_f32_e32 v62, v157, v182
	v_sub_f32_e32 v63, v63, v182
	v_sub_f32_e32 v50, v50, v182
	v_add_f32_e32 v53, v55, v53
	v_add_f32_e32 v55, v161, v58
	v_exp_f32_e32 v62, v62
	v_exp_f32_e32 v157, v63
	v_sub_f32_e32 v63, v154, v182
	v_exp_f32_e32 v154, v50
	v_sub_f32_e32 v50, v155, v182
	v_add_f32_e32 v53, v55, v53
	v_add_f32_e32 v55, v158, v59
	v_exp_f32_e32 v63, v63
	v_exp_f32_e32 v155, v50
	v_sub_f32_e32 v50, v51, v182
	v_add_f32_e32 v53, v55, v53
	v_add_f32_e32 v55, v159, v60
	v_exp_f32_e32 v184, v50
	v_add_f32_e32 v53, v55, v53
	v_add_f32_e32 v55, v156, v61
	v_add_f32_e32 v53, v55, v53
	v_add_f32_e32 v55, v157, v62
	v_add_f32_e32 v50, v55, v53
	v_add_f32_e32 v51, v154, v63
	v_add_f32_e32 v50, v51, v50
	v_add_f32_e32 v51, v184, v155
	v_add_f32_e32 v185, v51, v50
	v_fmac_f32_e32 v185, v173, v64
	v_cvt_pk_bf16_f32 v50, v65, v169
	v_cvt_pk_bf16_f32 v51, v166, v52
	v_cvt_pk_bf16_f32 v52, v164, v54
	v_cvt_pk_bf16_f32 v53, v162, v56
	v_cvt_pk_bf16_f32 v54, v168, v170
	v_cvt_pk_bf16_f32 v55, v183, v167
	v_cvt_pk_bf16_f32 v56, v181, v165
	v_cvt_pk_bf16_f32 v57, v171, v57
	v_cvt_pk_bf16_f32 v58, v160, v58
	v_cvt_pk_bf16_f32 v59, v59, v60
	v_cvt_pk_bf16_f32 v60, v61, v62
	v_cvt_pk_bf16_f32 v61, v63, v155
	v_cvt_pk_bf16_f32 v62, v163, v161
	v_cvt_pk_bf16_f32 v63, v158, v159
	v_cvt_pk_bf16_f32 v64, v156, v157
	v_cvt_pk_bf16_f32 v65, v154, v184
	v_mov_b32_e32 v173, v185
	ds_read_b64_tr_b16 v[202:203], v179 offset:36864
	ds_read_b64_tr_b16 v[204:205], v179 offset:38016
	ds_read_b64_tr_b16 v[206:207], v179 offset:36928
	ds_read_b64_tr_b16 v[208:209], v179 offset:38080
	ds_read_b64_tr_b16 v[210:211], v179 offset:39168
	ds_read_b64_tr_b16 v[212:213], v179 offset:40320
	ds_read_b64_tr_b16 v[220:221], v179 offset:39232
	ds_read_b64_tr_b16 v[222:223], v179 offset:40384
	ds_read_b64_tr_b16 v[224:225], v179 offset:41472
	ds_read_b64_tr_b16 v[226:227], v179 offset:42624
	ds_read_b64_tr_b16 v[228:229], v179 offset:41536
	ds_read_b64_tr_b16 v[230:231], v179 offset:42688
	ds_read_b64_tr_b16 v[232:233], v179 offset:43776
	ds_read_b64_tr_b16 v[234:235], v179 offset:44928
	ds_read_b64_tr_b16 v[236:237], v179 offset:43840
	ds_read_b64_tr_b16 v[238:239], v179 offset:44992
	s_branch .LBB0_1009

.LBB0_1015:
	s_and_b64 vcc, exec, s[8:9]
	s_cbranch_vccnz .LBB0_1017
	s_waitcnt lgkmcnt(0)
	v_mfma_f32_32x32x16_bf16 v[4:19], v[202:205], v[50:53], v[4:19]
	v_mfma_f32_32x32x16_bf16 v[26:41], v[206:209], v[50:53], v[26:41]
	v_mfma_f32_32x32x16_bf16 v[4:19], v[210:213], v[58:61], v[4:19]
	v_mfma_f32_32x32x16_bf16 v[26:41], v[220:223], v[58:61], v[26:41]
	v_mfma_f32_32x32x16_bf16 v[4:19], v[224:227], v[54:57], v[4:19]
	v_mfma_f32_32x32x16_bf16 v[26:41], v[228:231], v[54:57], v[26:41]
	v_mfma_f32_32x32x16_bf16 v[4:19], v[232:235], v[62:65], v[4:19]
	v_mfma_f32_32x32x16_bf16 v[26:41], v[236:239], v[62:65], v[26:41]
